# attention: bias via 2 aligned ds_read_b128 from 4 shifted table copies (mask folded into per-lane -m constants), batched prologue loads; GEMM: mode-1 epilogue fast path, folded canonicalizing v_max
# baseline (speedup 1.0000x reference)
.LBB0_108:
	v_readlane_b32 s0, v252, 17
	v_readlane_b32 s1, v252, 18
	s_andn2_b64 vcc, exec, s[0:1]
	s_cbranch_vccnz .LBB0_163
	v_and_b32_e32 v63, 15, v156
	s_waitcnt vmcnt(0)
	v_mad_u32_u24 v0, v63, s22, 0
	v_and_b32_e32 v1, 48, v156
	s_movk_i32 s0, 0x180
	s_lshl_b32 s8, s3, 4
	v_add_u32_e32 v67, v0, v1
	v_mad_u32_u24 v5, v63, s0, v0
	v_lshrrev_b32_e32 v0, 4, v154
	v_lshlrev_b32_e32 v56, 3, v0
	v_or_b32_e32 v2, s8, v63
	v_add_u32_e32 v4, s2, v56
	v_med3_u32 v3, v2, 8, 56
	v_or_b32_e32 v0, 6, v4
	v_add_u32_e32 v6, -8, v3
	v_add_u32_e32 v3, 8, v3
	v_cmp_ge_u32_e32 vcc, v0, v6
	v_cmp_lt_u32_e64 s[0:1], v0, v3
	v_sub_u32_e32 v0, v0, v2
	v_lshl_add_u32 v0, v0, 16, v215
	s_and_b64 vcc, vcc, s[0:1]
	v_or_b32_e32 v7, 7, v4
	v_cndmask_b32_e32 v0, v216, v0, vcc
	v_cmp_ge_u32_e32 vcc, v7, v6
	v_cmp_lt_u32_e64 s[0:1], v7, v3
	v_sub_u32_e32 v7, v7, v2
	v_lshl_add_u32 v7, v7, 24, v217
	s_and_b64 vcc, vcc, s[0:1]
	v_or_b32_e32 v8, 5, v4
	v_cndmask_b32_e32 v7, v218, v7, vcc
	v_cmp_ge_u32_e32 vcc, v8, v6
	v_cmp_lt_u32_e64 s[0:1], v8, v3
	v_sub_u32_e32 v8, v8, v2
	v_lshl_add_u32 v8, v8, 8, v219
	s_and_b64 vcc, vcc, s[0:1]
	v_or_b32_e32 v9, 4, v4
	v_cndmask_b32_e32 v8, v220, v8, vcc
	v_cmp_ge_u32_e32 vcc, v9, v6
	v_cmp_lt_u32_e64 s[0:1], v9, v3
	v_sub_u32_e32 v9, v9, v2
	v_add_u32_e32 v9, 15, v9
	s_and_b64 vcc, vcc, s[0:1]
	v_cndmask_b32_e32 v9, 31, v9, vcc
	v_or_b32_e32 v0, v7, v0
	v_or3_b32 v7, v0, v8, v9
	v_or_b32_e32 v0, 2, v4
	v_cmp_ge_u32_e32 vcc, v0, v6
	v_cmp_lt_u32_e64 s[0:1], v0, v3
	v_sub_u32_e32 v0, v0, v2
	v_lshl_add_u32 v0, v0, 16, v215
	s_and_b64 vcc, vcc, s[0:1]
	v_or_b32_e32 v8, 3, v4
	v_cndmask_b32_e32 v0, v216, v0, vcc
	v_cmp_ge_u32_e32 vcc, v8, v6
	v_cmp_lt_u32_e64 s[0:1], v8, v3
	v_sub_u32_e32 v8, v8, v2
	v_lshl_add_u32 v8, v8, 24, v217
	s_and_b64 vcc, vcc, s[0:1]
	v_or_b32_e32 v10, 1, v4
	v_cndmask_b32_e32 v8, v218, v8, vcc
	v_cmp_ge_u32_e32 vcc, v10, v6
	v_cmp_lt_u32_e64 s[0:1], v10, v3
	v_sub_u32_e32 v10, v10, v2
	v_lshl_add_u32 v10, v10, 8, v219
	s_and_b64 vcc, vcc, s[0:1]
	v_cndmask_b32_e32 v10, v220, v10, vcc
	v_cmp_ge_u32_e32 vcc, v4, v6
	v_cmp_lt_u32_e64 s[0:1], v4, v3
	v_sub_u32_e32 v2, v4, v2
	v_add_u32_e32 v2, 15, v2
	s_and_b64 vcc, vcc, s[0:1]
	v_cndmask_b32_e32 v6, 31, v2, vcc
	v_or_b32_e32 v0, v8, v0
	v_or3_b32 v8, v0, v10, v6
	v_and_b32_e32 v10, 7, v156
	v_ashrrev_i32_e32 v79, 3, v156
	v_lshlrev_b32_e32 v0, 4, v10
	v_mad_u64_u32 v[2:3], s[0:1], v79, s22, v[0:1]
	s_movk_i32 s0, 0x2d0
	s_ashr_i32 s9, s12, 8
	v_cmp_gt_i32_e64 s[36:37], s0, v156
	s_movk_i32 s0, 0x800
	v_add_u32_e32 v78, v5, v1
	v_cmp_gt_i32_e64 s[38:39], s0, v156
	s_lshl_b32 s0, s9, 6
	v_add_u32_e32 v1, 0, v1
	s_or_b32 s10, s8, s0
	v_add_u32_e32 v82, 0x12000, v1
	v_mul_i32_i24_e32 v1, 0xfffffe80, v63
	s_mov_b32 s0, 0x14400
	v_lshlrev_b32_e32 v3, 1, v154
	v_add3_u32 v83, v5, v1, s0
	v_readlane_b32 s0, v251, 2
	v_and_b32_e32 v3, 24, v3
	v_mov_b32_e32 v57, v153
	v_readlane_b32 s1, v251, 3
	v_add_u32_e32 v3, s2, v3
	v_readlane_b32 s2, v251, 6
	v_lshl_add_u64 v[60:61], s[0:1], 0, v[56:57]
	v_readlane_b32 s0, v249, 50
	v_and_b32_e32 v152, 48, v154
	v_readlane_b32 s3, v251, 7
	s_cmp_lt_u32 s0, 4
	v_lshlrev_b32_e32 v1, 4, v156
	v_readlane_b32 s0, v251, 8
	v_lshlrev_b32_e32 v80, 1, v4
	v_and_or_b32 v3, v156, 3, v3
	v_lshlrev_b32_e32 v4, 3, v10
	v_lshl_add_u64 v[58:59], s[2:3], 0, v[152:153]
	v_and_b32_e32 v152, 0x1f0, v1
	v_readlane_b32 s1, v251, 9
	v_mov_b32_e32 v1, v153
	v_mul_u32_u24_e32 v81, 0x90, v3
	s_cselect_b64 s[40:41], -1, 0
	v_add_u32_e32 v62, 0, v0
	v_lshl_add_u64 v[64:65], s[0:1], 0, v[152:153]
	v_add_u32_e32 v66, 0, v152
	v_and_b32_e32 v84, 0xff, v6
	v_and_b32_e32 v85, 0xff, v9
	v_bfe_u32 v86, v8, 8, 8
	v_bfe_u32 v87, v7, 8, 8
	v_bfe_u32 v88, v8, 16, 8
	v_bfe_u32 v89, v7, 16, 8
	v_lshrrev_b32_e32 v90, 24, v8
	v_lshrrev_b32_e32 v91, 24, v7
	s_mov_b32 s5, 0x20200
	v_lshrrev_b32_e32 v162, 1, v80
	v_subrev_u32_e32 v162, s8, v162
	v_sub_u32_e32 v162, v162, v63
	v_add_u32_e32 v162, 15, v162
	v_sub_u32_e32 v163, 0, v162
	v_and_b32_e32 v163, 3, v163
	v_add3_u32 v162, v162, v163, 16
	v_lshlrev_b32_e32 v162, 2, v162
	v_mul_u32_u24_e32 v163, 0xf00, v163
	v_add3_u32 v162, v162, v163, s5
	v_mov_b32_e32 v163, 0xf149f2ca
	v_cmp_eq_u32_e32 vcc, 31, v84
	v_mov_b32_e32 v84, 0x42c80000
	s_nop 0
	v_cndmask_b32_e32 v84, v84, v163, vcc
	v_cmp_eq_u32_e32 vcc, 31, v85
	v_mov_b32_e32 v85, 0x42c80000
	s_nop 0
	v_cndmask_b32_e32 v85, v85, v163, vcc
	v_cmp_eq_u32_e32 vcc, 31, v86
	v_mov_b32_e32 v86, 0x42c80000
	s_nop 0
	v_cndmask_b32_e32 v86, v86, v163, vcc
	v_cmp_eq_u32_e32 vcc, 31, v87
	v_mov_b32_e32 v87, 0x42c80000
	s_nop 0
	v_cndmask_b32_e32 v87, v87, v163, vcc
	v_cmp_eq_u32_e32 vcc, 31, v88
	v_mov_b32_e32 v88, 0x42c80000
	s_nop 0
	v_cndmask_b32_e32 v88, v88, v163, vcc
	v_cmp_eq_u32_e32 vcc, 31, v89
	v_mov_b32_e32 v89, 0x42c80000
	s_nop 0
	v_cndmask_b32_e32 v89, v89, v163, vcc
	v_cmp_eq_u32_e32 vcc, 31, v90
	v_mov_b32_e32 v90, 0x42c80000
	s_nop 0
	v_cndmask_b32_e32 v90, v90, v163, vcc
	v_cmp_eq_u32_e32 vcc, 31, v91
	v_mov_b32_e32 v91, 0x42c80000
	s_nop 0
	v_cndmask_b32_e32 v91, v91, v163, vcc
	v_lshl_add_u64 v[68:69], s[2:3], 0, v[0:1]
	v_lshlrev_b32_e32 v152, 1, v4
	v_add_u32_e32 v92, 0, v2
	s_mov_b32 s11, s28
	s_mov_b32 s12, s28
	s_branch .LBB0_111

.LBB0_111:
	s_barrier
	s_lshl_b32 s0, s12, 6
	s_ashr_i32 s14, s12, 4
	s_and_b32 s13, s0, 0x3c0
	s_mov_b32 s5, 0x20200
	s_and_b32 s4, s11, 15
	s_mulk_i32 s4, 0x1d1
	v_and_b32_e32 v0, 63, v156
	v_bfe_u32 v1, v156, 6, 2
	v_lshrrev_b32_e32 v2, 8, v156
	v_sub_u32_e32 v3, v0, v1
	v_add_u32_e32 v3, -16, v3
	v_med3_i32 v4, v3, 0, 30
	v_lshlrev_b32_e32 v5, 3, v2
	v_mad_u32_u24 v6, v5, 31, v4
	v_add_lshl_u32 v6, v6, s4, 2
	v_lshlrev_b32_e32 v7, 2, v0
	v_mul_u32_u24_e32 v16, 0xf00, v1
	v_lshl_add_u32 v7, v5, 8, v7
	v_add3_u32 v7, v7, v16, s5
	v_cmp_eq_u32_e32 vcc, 0, v2
	v_add_u32_e32 v17, 0x2e8, v6
	v_add_u32_e32 v18, 0x364, v6
	v_lshl_add_u32 v19, v1, 8, 0
	v_cndmask_b32_e32 v17, v17, v18, vcc
	v_lshl_add_u32 v19, v0, 2, v19
	v_add_u32_e32 v18, 0x700, v7
	v_cndmask_b32_e32 v19, v19, v18, vcc
	global_load_dword v8, v6, s[64:65] offset:0
	global_load_dword v9, v6, s[64:65] offset:124
	global_load_dword v10, v6, s[64:65] offset:248
	global_load_dword v11, v6, s[64:65] offset:372
	global_load_dword v12, v6, s[64:65] offset:496
	global_load_dword v13, v6, s[64:65] offset:620
	global_load_dword v14, v6, s[64:65] offset:744
	global_load_dword v15, v17, s[64:65]
	s_lshl_b32 s2, s14, 8
	s_lshl_b32 s26, s13, 1
	s_add_i32 s2, s2, 0x8000
	v_lshl_add_u64 v[16:17], v[68:69], 0, s[26:27]
	v_ashrrev_i32_e32 v18, 3, v156
	v_add_u32_e32 v20, s2, v18
	v_ashrrev_i32_e32 v21, 31, v20
	v_lshlrev_b64 v[20:21], 12, v[20:21]
	v_lshl_add_u64 v[20:21], v[16:17], 0, v[20:21]
	s_mov_b32 s16, 0x40000
	global_load_dwordx4 v[24:27], v[20:21], off offset:2048
	v_add_co_u32_e32 v20, vcc, s16, v20
	s_nop 1
	v_addc_co_u32_e32 v21, vcc, 0, v21, vcc
	global_load_dwordx4 v[28:31], v[20:21], off offset:2048
	v_add_co_u32_e32 v20, vcc, s16, v20
	s_nop 1
	v_addc_co_u32_e32 v21, vcc, 0, v21, vcc
	global_load_dwordx4 v[32:35], v[20:21], off offset:2048
	v_add_co_u32_e32 v20, vcc, s16, v20
	s_nop 1
	v_addc_co_u32_e32 v21, vcc, 0, v21, vcc
	global_load_dwordx4 v[36:39], v[20:21], off offset:2048
	v_lshlrev_b32_e32 v22, 2, v18
	v_lshrrev_b32_e32 v23, 1, v18
	v_and_b32_e32 v1, 0xfffffe3, v18
	v_and_b32_e32 v22, 16, v22
	v_and_b32_e32 v23, 12, v23
	v_or3_b32 v1, v1, v22, v23
	v_mad_u32_u24 v1, v1, s22, v62
	s_ashr_i32 s3, s2, 31
	v_lshl_add_u64 v[16:17], s[2:3], 1, v[64:65]
	v_ashrrev_i32_e32 v18, 5, v156
	v_add_u32_e32 v20, s13, v18
	v_mad_i64_i32 v[20:21], s[16:17], v20, s23, v[16:17]
	s_mov_b32 s4, 0x120000
	global_load_dwordx4 v[40:43], v[20:21], off
	v_add_co_u32_e32 v20, vcc, s4, v20
	s_nop 1
	v_addc_co_u32_e32 v21, vcc, 0, v21, vcc
	global_load_dwordx4 v[44:47], v[20:21], off
	v_add_co_u32_e32 v20, vcc, s4, v20
	s_nop 1
	v_addc_co_u32_e32 v21, vcc, 0, v21, vcc
	global_load_dwordx4 v[48:51], v[20:21], off
	v_add_co_u32_e32 v20, vcc, s4, v20
	s_nop 1
	v_addc_co_u32_e32 v21, vcc, 0, v21, vcc
	global_load_dwordx4 v[52:55], v[20:21], off
	s_movk_i32 s5, 0x210
	v_mad_u32_u24 v23, v18, s5, v66
	v_cmp_gt_u32_e64 s[2:3], 31, v3
	s_waitcnt vmcnt(8)
	v_mul_f32_e32 v8, 0x3fb8aa3b, v8
	v_cndmask_b32_e64 v8, 0, v8, s[2:3]
	v_mul_f32_e32 v9, 0x3fb8aa3b, v9
	v_cndmask_b32_e64 v9, 0, v9, s[2:3]
	v_mul_f32_e32 v10, 0x3fb8aa3b, v10
	v_cndmask_b32_e64 v10, 0, v10, s[2:3]
	v_mul_f32_e32 v11, 0x3fb8aa3b, v11
	v_cndmask_b32_e64 v11, 0, v11, s[2:3]
	v_mul_f32_e32 v12, 0x3fb8aa3b, v12
	v_cndmask_b32_e64 v12, 0, v12, s[2:3]
	v_mul_f32_e32 v13, 0x3fb8aa3b, v13
	v_cndmask_b32_e64 v13, 0, v13, s[2:3]
	v_mul_f32_e32 v14, 0x3fb8aa3b, v14
	v_cndmask_b32_e64 v14, 0, v14, s[2:3]
	v_mul_f32_e32 v15, 0x3fb8aa3b, v15
	v_cndmask_b32_e64 v15, 0, v15, s[2:3]
	ds_write_b32 v7, v8 offset:0
	ds_write_b32 v7, v9 offset:256
	ds_write_b32 v7, v10 offset:512
	ds_write_b32 v7, v11 offset:768
	ds_write_b32 v7, v12 offset:1024
	ds_write_b32 v7, v13 offset:1280
	ds_write_b32 v7, v14 offset:1536
	ds_write_b32 v19, v15
	s_waitcnt vmcnt(7)
	ds_write_b128 v1, v[24:27] offset:3072
	s_waitcnt vmcnt(6)
	ds_write_b128 v1, v[28:31] offset:12288
	s_waitcnt vmcnt(5)
	ds_write_b128 v1, v[32:35] offset:21504
	s_waitcnt vmcnt(4)
	ds_write_b128 v1, v[36:39] offset:30720
	s_waitcnt vmcnt(3)
	ds_write_b128 v23, v[40:43] offset:39936
	s_waitcnt vmcnt(2)
	ds_write_b128 v23, v[44:47] offset:48384
	s_waitcnt vmcnt(1)
	ds_write_b128 v23, v[48:51] offset:56832
	s_waitcnt vmcnt(0)
	ds_write_b128 v23, v[52:55] offset:65280
.LBB0_121:
	s_lshl_b32 s0, s14, 11
	s_waitcnt vmcnt(0)
	v_add_u32_e32 v0, s0, v79
	v_ashrrev_i32_e32 v1, 31, v0
	v_readlane_b32 s4, v251, 6
	v_lshlrev_b64 v[0:1], 12, v[0:1]
	v_readlane_b32 s5, v251, 7
	s_lshl_b32 s26, s13, 1
	v_readlane_b32 s2, v251, 8
	v_lshl_add_u64 v[0:1], s[4:5], 0, v[0:1]
	v_lshl_add_u64 v[0:1], v[0:1], 0, s[26:27]
	v_readlane_b32 s3, v251, 9
	v_lshl_add_u64 v[70:71], v[0:1], 0, v[152:153]
	v_add_u32_e32 v2, s13, v79
	v_mov_b64_e32 v[0:1], s[2:3]
	v_mad_i64_i32 v[0:1], s[2:3], v2, s23, v[0:1]
	s_ashr_i32 s1, s0, 31
	v_lshl_add_u64 v[0:1], s[0:1], 1, v[0:1]
	v_lshl_add_u64 v[72:73], v[0:1], 0, v[152:153]
	global_load_dwordx4 v[0:3], v[70:71], off offset:2048
	global_load_dwordx4 v[4:7], v[72:73], off
	global_load_dwordx4 v[8:11], v[72:73], off offset:128
	s_mov_b32 s1, 0x40000
	v_add_co_u32_e32 v12, vcc, s1, v70
	s_add_i32 s2, s10, s0
	s_nop 0
	v_addc_co_u32_e32 v13, vcc, 0, v71, vcc
	global_load_dwordx4 v[12:15], v[12:13], off offset:2048
	v_or_b32_e32 v20, s2, v63
	v_ashrrev_i32_e32 v21, 31, v20
	v_add_co_u32_e32 v24, vcc, s25, v70
	v_lshlrev_b64 v[20:21], 12, v[20:21]
	s_nop 0
	v_addc_co_u32_e32 v25, vcc, 0, v71, vcc
	v_lshl_add_u64 v[20:21], s[4:5], 0, v[20:21]
	v_add_co_u32_e32 v26, vcc, s31, v70
	v_add_u32_e32 v96, 0x18c00, v92
	v_lshl_add_u64 v[20:21], v[20:21], 0, s[26:27]
	v_addc_co_u32_e32 v27, vcc, 0, v71, vcc
	v_add_u32_e32 v93, 0x12000, v92
	v_add_u32_e32 v94, 0x14400, v92
	v_add_u32_e32 v95, 0x16800, v92
	global_load_dwordx4 v[16:19], v[72:73], off offset:256
	v_lshl_add_u64 v[32:33], v[56:57], 1, v[20:21]
	global_load_dwordx4 v[20:23], v[72:73], off offset:384
	global_load_dwordx4 v[28:31], v[24:25], off offset:2048
	s_nop 0
	global_load_dwordx4 v[24:27], v[26:27], off offset:2048
	v_mov_b32_e32 v100, 0
	s_mov_b32 s1, 0
	s_or_b32 s0, s0, s8
	v_lshl_add_u64 v[74:75], v[58:59], 0, s[26:27]
	v_lshl_add_u64 v[76:77], v[60:61], 0, s[26:27]
	v_mov_b32_e32 v101, 0xf149f2ca
	s_mov_b32 s15, 4
	s_mov_b32 s5, 8
	s_mov_b32 s3, -3
	v_mov_b32_e32 v97, 0
	v_mov_b32_e32 v98, 8
	v_mov_b32_e32 v99, 0
	s_mov_b32 s14, 0
	s_mov_b32 s13, s9
	s_mov_b32 s4, 0
	s_mov_b32 s16, 4
	v_mov_b32_e32 v34, v100
	v_mov_b32_e32 v35, v100
	v_mov_b32_e32 v36, v100
	v_mov_b32_e32 v37, v100
	v_mov_b32_e32 v38, v100
	v_mov_b32_e32 v39, v100
	v_mov_b32_e32 v40, v100
	v_mov_b32_e32 v41, v100
	v_mov_b32_e32 v42, v100
	v_mov_b32_e32 v43, v100
	v_mov_b32_e32 v44, v100
	v_mov_b32_e32 v45, v100
	v_mov_b32_e32 v46, v100
	v_mov_b32_e32 v47, v100
	s_waitcnt vmcnt(0)
	ds_write_b128 v96, v[8:11]
	ds_write_b128 v94, v[4:7]
	ds_write_b128 v93, v[0:3]
	s_waitcnt vmcnt(4)
	ds_write_b128 v95, v[12:15]
	s_waitcnt lgkmcnt(0)
	s_barrier
	global_load_dwordx4 v[0:3], v[32:33], off
	global_load_dwordx4 v[4:7], v[32:33], off offset:64
	v_mov_b32_e32 v8, v153
	v_mov_b32_e32 v9, v153
	v_mov_b32_e32 v10, v153
	v_mov_b32_e32 v11, v153
	v_mov_b32_e32 v12, v153
	v_mov_b32_e32 v13, v153
	v_mov_b32_e32 v14, v153
	v_mov_b32_e32 v15, v153
	v_mov_b32_e32 v32, 0
	v_mov_b32_e32 v33, v100
	v_add_u32_e32 v210, v82, v81
	v_add_u32_e32 v211, v83, v80
	v_add_u32_e32 v226, 0x1b000, v92
	v_add_u32_e32 v227, 0x1d400, v92
	v_mov_b32_e32 v144, 0x3f803f80
	v_mov_b32_e32 v145, v144
	v_mov_b32_e32 v146, v144
	v_mov_b32_e32 v147, v144
	v_sub_u32_e32 v102, v97, v99
	v_add_u32_e32 v102, s14, v102
	v_cmp_gt_u32_e32 vcc, 8, v102
	s_cbranch_vccz .Lpf_skip_init
	v_mad_u32_u24 v103, v102, s34, v67
	v_subrev_u32_e32 v120, s13, v99
	ds_read_b128 v[166:169], v103 offset:3072
	ds_read_b128 v[174:177], v103 offset:5376
	ds_read_b128 v[170:173], v103 offset:3136
	ds_read_b128 v[178:181], v103 offset:5440
	v_add3_u32 v120, v120, v102, 7
	ds_read_b128 v[182:185], v210 offset:0
	ds_read_b128 v[190:193], v210 offset:576
	ds_read_b128 v[186:189], v210 offset:64
	ds_read_b128 v[194:197], v210 offset:640
	v_lshl_add_u32 v120, v120, 8, v162
	ds_read_b128 v[112:115], v120
	ds_read_b128 v[116:119], v120 offset:16
	s_waitcnt lgkmcnt(10)
	s_branch .Lpf_done_init

.LBB0_122:
	s_waitcnt vmcnt(4)
	ds_write_b128 v95, v[48:51]
	ds_write_b128 v96, v[52:55]
	v_sub_u32_e32 v102, v97, v99
	v_add_u32_e32 v102, s14, v102
	v_cmp_gt_u32_e32 vcc, 8, v102
	s_cbranch_vccz .Lpf_skip_a
	v_mad_u32_u24 v103, v102, s34, v67
	v_subrev_u32_e32 v120, s13, v99
	ds_read_b128 v[166:169], v103 offset:3072
	ds_read_b128 v[174:177], v103 offset:5376
	ds_read_b128 v[170:173], v103 offset:3136
	ds_read_b128 v[178:181], v103 offset:5440
	v_add3_u32 v120, v120, v102, 7
	ds_read_b128 v[182:185], v210 offset:0
	ds_read_b128 v[190:193], v210 offset:576
	ds_read_b128 v[186:189], v210 offset:64
	ds_read_b128 v[194:197], v210 offset:640
	v_lshl_add_u32 v120, v120, 8, v162
	ds_read_b128 v[112:115], v120
	ds_read_b128 v[116:119], v120 offset:16
	s_waitcnt lgkmcnt(10)
	s_branch .Lpf_done_a

.LBB0_133:
	s_cmp_lt_i32 s4, 16
	s_cselect_b32 s18, s15, 0
	s_ashr_i32 s19, s18, 31
	s_lshl_b64 s[20:21], s[18:19], 18
	s_lshl_b32 s18, s18, 6
	s_ashr_i32 s19, s18, 31
	s_waitcnt vmcnt(4)
	ds_write_b128 v226, v[28:31]
	ds_write_b128 v227, v[16:19]
	v_sub_u32_e32 v102, v97, v99
	v_add_u32_e32 v102, s14, v102
	v_cmp_gt_u32_e32 vcc, 8, v102
	s_cbranch_vccz .Lpf_skip_b
	v_mad_u32_u24 v103, v102, s34, v67
	v_subrev_u32_e32 v120, s13, v99
	ds_read_b128 v[166:169], v103 offset:3072
	ds_read_b128 v[174:177], v103 offset:5376
	ds_read_b128 v[170:173], v103 offset:3136
	ds_read_b128 v[178:181], v103 offset:5440
	v_add3_u32 v120, v120, v102, 7
	ds_read_b128 v[182:185], v210 offset:18432
	ds_read_b128 v[190:193], v210 offset:19008
	ds_read_b128 v[186:189], v210 offset:18496
	ds_read_b128 v[194:197], v210 offset:19072
	v_lshl_add_u32 v120, v120, 8, v162
	ds_read_b128 v[112:115], v120
	ds_read_b128 v[116:119], v120 offset:16
	s_waitcnt lgkmcnt(10)
	s_branch .Lpf_done_b

.LBB0_143:
	s_cmp_lt_i32 s4, 16
	s_cselect_b32 s18, s16, 0
	s_ashr_i32 s19, s18, 31
	s_lshl_b64 s[20:21], s[18:19], 18
	s_lshl_b32 s18, s18, 6
	s_ashr_i32 s19, s18, 31
	s_waitcnt vmcnt(4)
	ds_write_b128 v93, v[24:27]
	ds_write_b128 v94, v[20:23]
	v_sub_u32_e32 v102, v97, v99
	v_add_u32_e32 v102, s14, v102
	v_cmp_gt_u32_e32 vcc, 8, v102
	s_cbranch_vccz .Lpf_skip_c
	v_mad_u32_u24 v103, v102, s34, v67
	v_subrev_u32_e32 v120, s13, v99
	ds_read_b128 v[166:169], v103 offset:3072
	ds_read_b128 v[174:177], v103 offset:5376
	ds_read_b128 v[170:173], v103 offset:3136
	ds_read_b128 v[178:181], v103 offset:5440
	v_add3_u32 v120, v120, v102, 7
	ds_read_b128 v[182:185], v210 offset:36864
	ds_read_b128 v[190:193], v210 offset:37440
	ds_read_b128 v[186:189], v210 offset:36928
	ds_read_b128 v[194:197], v210 offset:37504
	v_lshl_add_u32 v120, v120, 8, v162
	ds_read_b128 v[112:115], v120
	ds_read_b128 v[116:119], v120 offset:16
	s_waitcnt lgkmcnt(10)
	s_branch .Lpf_done_c

.Lrare_a:
	v_mov_b32_e32 v122, v121
	s_nop 1
	v_permlane16_swap_b32_e32 v121, v122
	v_max_f32_e32 v121, v121, v122
	v_mov_b32_e32 v122, v121
	s_nop 1
	v_permlane32_swap_b32_e32 v121, v122
	v_max3_f32 v121, v121, v122, 0
	v_exp_f32_e64 v164, -v121
	v_sub_f32_e32 v104, v104, v121
	v_sub_f32_e32 v105, v105, v121
	v_sub_f32_e32 v106, v106, v121
	v_sub_f32_e32 v107, v107, v121
	v_sub_f32_e32 v108, v108, v121
	v_sub_f32_e32 v109, v109, v121
	v_sub_f32_e32 v110, v110, v121
	v_sub_f32_e32 v111, v111, v121
	v_sub_f32_e32 v112, v112, v121
	v_sub_f32_e32 v113, v113, v121
	v_sub_f32_e32 v114, v114, v121
	v_sub_f32_e32 v115, v115, v121
	v_sub_f32_e32 v116, v116, v121
	v_sub_f32_e32 v117, v117, v121
	v_sub_f32_e32 v118, v118, v121
	v_sub_f32_e32 v119, v119, v121
	v_sub_f32_e32 v140, v140, v121
	v_sub_f32_e32 v141, v141, v121
	v_sub_f32_e32 v142, v142, v121
	v_sub_f32_e32 v143, v143, v121
	v_sub_f32_e32 v148, v148, v121
	v_sub_f32_e32 v149, v149, v121
	v_sub_f32_e32 v150, v150, v121
	v_sub_f32_e32 v151, v151, v121
	v_sub_f32_e32 v158, v158, v121
	v_sub_f32_e32 v159, v159, v121
	v_sub_f32_e32 v160, v160, v121
	v_sub_f32_e32 v161, v161, v121
	v_mul_f32_e32 v32, v32, v164
	v_mul_f32_e32 v33, v33, v164
	v_mul_f32_e32 v34, v34, v164
	v_mul_f32_e32 v35, v35, v164
	v_mul_f32_e32 v36, v36, v164
	v_mul_f32_e32 v37, v37, v164
	v_mul_f32_e32 v38, v38, v164
	v_mul_f32_e32 v39, v39, v164
	v_mul_f32_e32 v40, v40, v164
	v_mul_f32_e32 v41, v41, v164
	v_mul_f32_e32 v42, v42, v164
	v_mul_f32_e32 v43, v43, v164
	v_mul_f32_e32 v44, v44, v164
	v_mul_f32_e32 v45, v45, v164
	v_mul_f32_e32 v46, v46, v164
	v_mul_f32_e32 v47, v47, v164
	v_mul_f32_e32 v132, v132, v164
	v_mul_f32_e32 v133, v133, v164
	v_mul_f32_e32 v134, v134, v164
	v_mul_f32_e32 v135, v135, v164
	s_branch .Lback_a

.LBB0_152:
	v_lshl_add_u32 v137, v102, 6, v78
	ds_read_b128 v[198:201], v137 offset:39936
	ds_read_b128 v[202:205], v137 offset:48384
	ds_read_b128 v[206:209], v137 offset:56832
	ds_read_b128 v[232:235], v137 offset:65280
	s_waitcnt lgkmcnt(4)
	v_mfma_f32_16x16x32_bf16 v[104:107], v[166:169], v[8:11], v[140:143]
	v_add_f32_e32 v112, v112, v148
	v_add_f32_e32 v113, v113, v149
	v_mfma_f32_16x16x32_bf16 v[108:111], v[174:177], v[8:11], v[140:143]
	v_add_f32_e32 v114, v114, v150
	v_add_f32_e32 v115, v115, v151
	v_mfma_f32_16x16x32_bf16 v[104:107], v[170:173], v[12:15], v[104:107]
	v_add_f32_e32 v116, v116, v158
	v_add_f32_e32 v117, v117, v159
	v_mfma_f32_16x16x32_bf16 v[108:111], v[178:181], v[12:15], v[108:111]
	v_add_f32_e32 v118, v118, v160
	v_add_f32_e32 v119, v119, v161
	ds_read_b128 v[236:239], v211 offset:0
	ds_read_b128 v[240:243], v211 offset:2304
	ds_read_b128 v[244:247], v211 offset:4608
	ds_read_b128 v[228:231], v211 offset:6912
	v_mfma_f32_16x16x32_bf16 v[112:115], v[182:185], v[8:11], v[112:115]
	v_mfma_f32_16x16x32_bf16 v[116:119], v[190:193], v[8:11], v[116:119]
	v_mfma_f32_16x16x32_bf16 v[112:115], v[186:189], v[12:15], v[112:115]
	v_mfma_f32_16x16x32_bf16 v[116:119], v[194:197], v[12:15], v[116:119]
	v_max3_f32 v121, v104, v105, v106
	v_max3_f32 v122, v108, v109, v110
	v_max3_f32 v121, v121, v107, v111
	s_nop 3
	v_max3_f32 v123, v112, v113, v114
	v_max3_f32 v122, v122, v116, v117
	v_max3_f32 v121, v121, v115, v118
	v_max3_f32 v121, v121, v122, v123
	v_max_f32_e32 v121, v121, v119
	v_cmp_lt_f32_e32 vcc, 0x41000000, v121
	s_cbranch_vccnz .Lrare_a

.LBB0_154:
	v_lshl_add_u32 v137, v102, 6, v78
	ds_read_b128 v[198:201], v137 offset:39936
	ds_read_b128 v[202:205], v137 offset:48384
	ds_read_b128 v[206:209], v137 offset:56832
	ds_read_b128 v[232:235], v137 offset:65280
	s_waitcnt lgkmcnt(4)
	v_mfma_f32_16x16x32_bf16 v[104:107], v[166:169], v[8:11], v[140:143]
	v_add_f32_e32 v112, v112, v148
	v_add_f32_e32 v113, v113, v149
	v_mfma_f32_16x16x32_bf16 v[108:111], v[174:177], v[8:11], v[140:143]
	v_add_f32_e32 v114, v114, v150
	v_add_f32_e32 v115, v115, v151
	v_mfma_f32_16x16x32_bf16 v[104:107], v[170:173], v[12:15], v[104:107]
	v_add_f32_e32 v116, v116, v158
	v_add_f32_e32 v117, v117, v159
	v_mfma_f32_16x16x32_bf16 v[108:111], v[178:181], v[12:15], v[108:111]
	v_add_f32_e32 v118, v118, v160
	v_add_f32_e32 v119, v119, v161
	ds_read_b128 v[236:239], v211 offset:18432
	ds_read_b128 v[240:243], v211 offset:20736
	ds_read_b128 v[244:247], v211 offset:23040
	ds_read_b128 v[228:231], v211 offset:25344
	v_mfma_f32_16x16x32_bf16 v[112:115], v[182:185], v[8:11], v[112:115]
	v_mfma_f32_16x16x32_bf16 v[116:119], v[190:193], v[8:11], v[116:119]
	v_mfma_f32_16x16x32_bf16 v[112:115], v[186:189], v[12:15], v[112:115]
	v_mfma_f32_16x16x32_bf16 v[116:119], v[194:197], v[12:15], v[116:119]
	v_max3_f32 v121, v104, v105, v106
	v_max3_f32 v122, v108, v109, v110
	v_max3_f32 v121, v121, v107, v111
	s_nop 3
	v_max3_f32 v123, v112, v113, v114
	v_max3_f32 v122, v122, v116, v117
	v_max3_f32 v121, v121, v115, v118
	v_max3_f32 v121, v121, v122, v123
	v_max_f32_e32 v121, v121, v119
	v_cmp_lt_f32_e32 vcc, 0x41000000, v121
	s_cbranch_vccnz .Lrare_b

.LBB0_156:
	v_lshl_add_u32 v137, v102, 6, v78
	ds_read_b128 v[198:201], v137 offset:39936
	ds_read_b128 v[202:205], v137 offset:48384
	ds_read_b128 v[206:209], v137 offset:56832
	ds_read_b128 v[232:235], v137 offset:65280
	s_waitcnt lgkmcnt(4)
	v_mfma_f32_16x16x32_bf16 v[104:107], v[166:169], v[8:11], v[140:143]
	v_add_f32_e32 v112, v112, v148
	v_add_f32_e32 v113, v113, v149
	v_mfma_f32_16x16x32_bf16 v[108:111], v[174:177], v[8:11], v[140:143]
	v_add_f32_e32 v114, v114, v150
	v_add_f32_e32 v115, v115, v151
	v_mfma_f32_16x16x32_bf16 v[104:107], v[170:173], v[12:15], v[104:107]
	v_add_f32_e32 v116, v116, v158
	v_add_f32_e32 v117, v117, v159
	v_mfma_f32_16x16x32_bf16 v[108:111], v[178:181], v[12:15], v[108:111]
	v_add_f32_e32 v118, v118, v160
	v_add_f32_e32 v119, v119, v161
	ds_read_b128 v[236:239], v211 offset:36864
	ds_read_b128 v[240:243], v211 offset:39168
	ds_read_b128 v[244:247], v211 offset:41472
	ds_read_b128 v[228:231], v211 offset:43776
	v_mfma_f32_16x16x32_bf16 v[112:115], v[182:185], v[8:11], v[112:115]
	v_mfma_f32_16x16x32_bf16 v[116:119], v[190:193], v[8:11], v[116:119]
	v_mfma_f32_16x16x32_bf16 v[112:115], v[186:189], v[12:15], v[112:115]
	v_mfma_f32_16x16x32_bf16 v[116:119], v[194:197], v[12:15], v[116:119]
	v_max3_f32 v121, v104, v105, v106
	v_max3_f32 v122, v108, v109, v110
	v_max3_f32 v121, v121, v107, v111
	s_nop 3
	v_max3_f32 v123, v112, v113, v114
	v_max3_f32 v122, v122, v116, v117
	v_max3_f32 v121, v121, v115, v118
	v_max3_f32 v121, v121, v122, v123
	v_max_f32_e32 v121, v121, v119
	v_cmp_lt_f32_e32 vcc, 0x41000000, v121
	s_cbranch_vccnz .Lrare_c

.LBB0_159:
	v_mov_b32_e32 v100, 0
	s_waitcnt vmcnt(2)
	v_mov_b64_e32 v[14:15], v[6:7]
	v_mov_b32_e32 v101, 0xf149f2ca
	v_mov_b32_e32 v132, 0
	v_mov_b32_e32 v133, 0
	v_mov_b32_e32 v134, 0
	v_mov_b32_e32 v135, 0
	v_mov_b32_e32 v140, 0x42c80000
	v_mov_b32_e32 v141, 0x42c80000
	v_mov_b32_e32 v142, 0x42c80000
	v_mov_b32_e32 v143, 0x42c80000
	v_mov_b32_e32 v148, v84
	v_mov_b32_e32 v149, v86
	v_mov_b32_e32 v150, v88
	v_mov_b32_e32 v151, v90
	v_mov_b32_e32 v158, v85
	v_mov_b32_e32 v159, v87
	v_mov_b32_e32 v160, v89
	v_mov_b32_e32 v161, v91
	v_mov_b64_e32 v[12:13], v[4:5]
	v_mov_b64_e32 v[10:11], v[2:3]
	v_mov_b64_e32 v[8:9], v[0:1]
	v_mov_b32_e32 v32, 0
	v_mov_b32_e32 v33, v100
	v_mov_b32_e32 v34, v100
	v_mov_b32_e32 v35, v100
	v_mov_b32_e32 v36, v100
	v_mov_b32_e32 v37, v100
	v_mov_b32_e32 v38, v100
	v_mov_b32_e32 v39, v100
	v_mov_b32_e32 v40, v100
	v_mov_b32_e32 v41, v100
	v_mov_b32_e32 v42, v100
	v_mov_b32_e32 v43, v100
	v_mov_b32_e32 v44, v100
	v_mov_b32_e32 v45, v100
	v_mov_b32_e32 v46, v100
	v_mov_b32_e32 v47, v100
	s_add_i32 s16, s5, -2
	s_cmp_lg_u32 s14, s16
	s_cbranch_scc0 .LBB0_128
	s_branch .LBB0_129
.LBB0_160:
	v_mov_b32_e32 v100, 0
	s_waitcnt vmcnt(2)
	v_mov_b64_e32 v[14:15], v[6:7]
	v_mov_b32_e32 v101, 0xf149f2ca
	v_mov_b32_e32 v132, 0
	v_mov_b32_e32 v133, 0
	v_mov_b32_e32 v134, 0
	v_mov_b32_e32 v135, 0
	v_mov_b32_e32 v140, 0x42c80000
	v_mov_b32_e32 v141, 0x42c80000
	v_mov_b32_e32 v142, 0x42c80000
	v_mov_b32_e32 v143, 0x42c80000
	v_mov_b32_e32 v148, v84
	v_mov_b32_e32 v149, v86
	v_mov_b32_e32 v150, v88
	v_mov_b32_e32 v151, v90
	v_mov_b32_e32 v158, v85
	v_mov_b32_e32 v159, v87
	v_mov_b32_e32 v160, v89
	v_mov_b32_e32 v161, v91
	v_mov_b64_e32 v[12:13], v[4:5]
	v_mov_b64_e32 v[10:11], v[2:3]
	v_mov_b64_e32 v[8:9], v[0:1]
	v_mov_b32_e32 v32, 0
	v_mov_b32_e32 v33, v100
	v_mov_b32_e32 v34, v100
	v_mov_b32_e32 v35, v100
	v_mov_b32_e32 v36, v100
	v_mov_b32_e32 v37, v100
	v_mov_b32_e32 v38, v100
	v_mov_b32_e32 v39, v100
	v_mov_b32_e32 v40, v100
	v_mov_b32_e32 v41, v100
	v_mov_b32_e32 v42, v100
	v_mov_b32_e32 v43, v100
	v_mov_b32_e32 v44, v100
	v_mov_b32_e32 v45, v100
	v_mov_b32_e32 v46, v100
	v_mov_b32_e32 v47, v100
	s_add_i32 s15, s5, -2
	s_cmp_lg_u32 s14, s15
	s_cbranch_scc0 .LBB0_138
	s_branch .LBB0_139
.LBB0_161:
	v_mov_b32_e32 v100, 0
	s_waitcnt vmcnt(2)
	v_mov_b64_e32 v[14:15], v[6:7]
	v_mov_b32_e32 v101, 0xf149f2ca
	v_mov_b32_e32 v132, 0
	v_mov_b32_e32 v133, 0
	v_mov_b32_e32 v134, 0
	v_mov_b32_e32 v135, 0
	v_mov_b32_e32 v140, 0x42c80000
	v_mov_b32_e32 v141, 0x42c80000
	v_mov_b32_e32 v142, 0x42c80000
	v_mov_b32_e32 v143, 0x42c80000
	v_mov_b32_e32 v148, v84
	v_mov_b32_e32 v149, v86
	v_mov_b32_e32 v150, v88
	v_mov_b32_e32 v151, v90
	v_mov_b32_e32 v158, v85
	v_mov_b32_e32 v159, v87
	v_mov_b32_e32 v160, v89
	v_mov_b32_e32 v161, v91
	v_mov_b64_e32 v[12:13], v[4:5]
	v_mov_b64_e32 v[10:11], v[2:3]
	v_mov_b64_e32 v[8:9], v[0:1]
	v_mov_b32_e32 v32, 0
	v_mov_b32_e32 v33, v100
	v_mov_b32_e32 v34, v100
	v_mov_b32_e32 v35, v100
	v_mov_b32_e32 v36, v100
	v_mov_b32_e32 v37, v100
	v_mov_b32_e32 v38, v100
	v_mov_b32_e32 v39, v100
	v_mov_b32_e32 v40, v100
	v_mov_b32_e32 v41, v100
	v_mov_b32_e32 v42, v100
	v_mov_b32_e32 v43, v100
	v_mov_b32_e32 v44, v100
	v_mov_b32_e32 v45, v100
	v_mov_b32_e32 v46, v100
	v_mov_b32_e32 v47, v100
	s_add_i32 s17, s5, -2
	s_cmp_lg_u32 s14, s17
	s_cbranch_scc0 .LBB0_148
	s_branch .LBB0_149

.LBB0_393:
	s_and_b64 vcc, exec, s[44:45]
	s_cbranch_vccz .LBB0_405
	s_and_b64 vcc, s[58:59], s[60:61]
	s_cbranch_vccnz .Lepi1_fast
	s_add_i32 s23, s22, s62
	v_mov_b32_e32 v136, 0
	v_cndmask_b32_e64 v128, 0, 1, s[58:59]
	v_lshl_add_u32 v144, v226, 2, s23
	v_cmp_ne_u32_e64 s[46:47], 1, v128
	s_andn2_b64 vcc, exec, s[58:59]
	v_mov_b32_e32 v140, 0
	v_mov_b32_e32 v141, v136
	v_mov_b32_e32 v142, 0
	v_mov_b32_e32 v143, 0
	s_cbranch_vccnz .LBB0_396
	ds_read_b128 v[140:143], v144 offset:1024

.Lepi1_fast:
	s_add_i32 s23, s22, s62
	v_lshl_add_u32 v184, v226, 2, s23
	ds_read_b128 v[140:143], v184 offset:1024
	ds_read_b128 v[136:139], v184 offset:1040
	ds_read_b128 v[132:135], v184 offset:1536
	ds_read_b128 v[128:131], v184 offset:1552
	s_lshl_b32 s23, s91, 2
	s_add_i32 s23, s22, s23
	v_lshl_add_u32 v152, v157, 2, s23
	ds_read_b32 v144, v152
	ds_read_b32 v146, v152 offset:64
	ds_read_b32 v148, v152 offset:128
	ds_read_b32 v150, v152 offset:192
	ds_read_b32 v176, v152 offset:512
	ds_read_b32 v178, v152 offset:576
	ds_read_b32 v180, v152 offset:640
	ds_read_b32 v182, v152 offset:704
	v_mul_lo_u32 v185, v174, s10
	v_lshl_or_b32 v184, s56, 8, v228
	v_add_lshl_u32 v184, v185, v184, 1
	s_mov_b64 s[22:23], s[78:79]
	s_lshl_b32 s46, s10, 5
	s_waitcnt lgkmcnt(0)
	v_fmamk_f32 v144, v144, 0x3a800000, v214
	v_fmamk_f32 v146, v146, 0x3a800000, v214
	v_fmamk_f32 v148, v148, 0x3a800000, v214
	v_fmamk_f32 v150, v150, 0x3a800000, v214
	v_fmamk_f32 v176, v176, 0x3a800000, v214
	v_fmamk_f32 v178, v178, 0x3a800000, v214
	v_fmamk_f32 v180, v180, 0x3a800000, v214
	v_fmamk_f32 v182, v182, 0x3a800000, v214
	v_rsq_f32_e32 v144, v144
	v_rsq_f32_e32 v146, v146
	v_rsq_f32_e32 v148, v148
	v_rsq_f32_e32 v150, v150
	v_rsq_f32_e32 v176, v176
	v_rsq_f32_e32 v178, v178
	v_rsq_f32_e32 v180, v180
	v_rsq_f32_e32 v182, v182
	v_pk_fma_f32 v[16:17], v[16:17], v[144:145], v[140:141] op_sel_hi:[1,0,1]
	v_pk_fma_f32 v[18:19], v[18:19], v[144:145], v[142:143] op_sel_hi:[1,0,1]
	v_pk_fma_f32 v[28:29], v[28:29], v[144:145], v[136:137] op_sel_hi:[1,0,1]
	v_pk_fma_f32 v[30:31], v[30:31], v[144:145], v[138:139] op_sel_hi:[1,0,1]
	v_max_f32_e32 v16, 0, v16
	v_max_f32_e32 v17, 0, v17
	v_max_f32_e32 v18, 0, v18
	v_max_f32_e32 v19, 0, v19
	v_max_f32_e32 v28, 0, v28
	v_max_f32_e32 v29, 0, v29
	v_max_f32_e32 v30, 0, v30
	v_max_f32_e32 v31, 0, v31
	v_pk_mul_f32 v[16:17], v[16:17], v[16:17]
	v_pk_mul_f32 v[18:19], v[18:19], v[18:19]
	v_pk_mul_f32 v[28:29], v[28:29], v[28:29]
	v_pk_mul_f32 v[30:31], v[30:31], v[30:31]
	v_cvt_pk_bf16_f32 v16, v16, v17
	v_cvt_pk_bf16_f32 v17, v18, v19
	v_cvt_pk_bf16_f32 v18, v28, v29
	v_cvt_pk_bf16_f32 v19, v30, v31
	global_store_dwordx4 v184, v[16:19], s[22:23]
	v_pk_fma_f32 v[24:25], v[24:25], v[144:145], v[132:133] op_sel_hi:[1,0,1]
	v_pk_fma_f32 v[26:27], v[26:27], v[144:145], v[134:135] op_sel_hi:[1,0,1]
	v_pk_fma_f32 v[20:21], v[20:21], v[144:145], v[128:129] op_sel_hi:[1,0,1]
	v_pk_fma_f32 v[22:23], v[22:23], v[144:145], v[130:131] op_sel_hi:[1,0,1]
	v_max_f32_e32 v24, 0, v24
	v_max_f32_e32 v25, 0, v25
	v_max_f32_e32 v26, 0, v26
	v_max_f32_e32 v27, 0, v27
	v_max_f32_e32 v20, 0, v20
	v_max_f32_e32 v21, 0, v21
	v_max_f32_e32 v22, 0, v22
	v_max_f32_e32 v23, 0, v23
	v_pk_mul_f32 v[24:25], v[24:25], v[24:25]
	v_pk_mul_f32 v[26:27], v[26:27], v[26:27]
	v_pk_mul_f32 v[20:21], v[20:21], v[20:21]
	v_pk_mul_f32 v[22:23], v[22:23], v[22:23]
	v_cvt_pk_bf16_f32 v24, v24, v25
	v_cvt_pk_bf16_f32 v25, v26, v27
	v_cvt_pk_bf16_f32 v26, v20, v21
	v_cvt_pk_bf16_f32 v27, v22, v23
	global_store_dwordx4 v184, v[24:27], s[22:23] offset:256
	s_add_u32 s22, s22, s46
	s_addc_u32 s23, s23, 0
	v_pk_fma_f32 v[12:13], v[12:13], v[146:147], v[140:141] op_sel_hi:[1,0,1]
	v_pk_fma_f32 v[14:15], v[14:15], v[146:147], v[142:143] op_sel_hi:[1,0,1]
	v_pk_fma_f32 v[8:9], v[8:9], v[146:147], v[136:137] op_sel_hi:[1,0,1]
	v_pk_fma_f32 v[10:11], v[10:11], v[146:147], v[138:139] op_sel_hi:[1,0,1]
	v_max_f32_e32 v12, 0, v12
	v_max_f32_e32 v13, 0, v13
	v_max_f32_e32 v14, 0, v14
	v_max_f32_e32 v15, 0, v15
	v_max_f32_e32 v8, 0, v8
	v_max_f32_e32 v9, 0, v9
	v_max_f32_e32 v10, 0, v10
	v_max_f32_e32 v11, 0, v11
	v_pk_mul_f32 v[12:13], v[12:13], v[12:13]
	v_pk_mul_f32 v[14:15], v[14:15], v[14:15]
	v_pk_mul_f32 v[8:9], v[8:9], v[8:9]
	v_pk_mul_f32 v[10:11], v[10:11], v[10:11]
	v_cvt_pk_bf16_f32 v12, v12, v13
	v_cvt_pk_bf16_f32 v13, v14, v15
	v_cvt_pk_bf16_f32 v14, v8, v9
	v_cvt_pk_bf16_f32 v15, v10, v11
	global_store_dwordx4 v184, v[12:15], s[22:23]
	v_pk_fma_f32 v[4:5], v[4:5], v[146:147], v[132:133] op_sel_hi:[1,0,1]
	v_pk_fma_f32 v[6:7], v[6:7], v[146:147], v[134:135] op_sel_hi:[1,0,1]
	v_pk_fma_f32 v[0:1], v[0:1], v[146:147], v[128:129] op_sel_hi:[1,0,1]
	v_pk_fma_f32 v[2:3], v[2:3], v[146:147], v[130:131] op_sel_hi:[1,0,1]
	v_max_f32_e32 v4, 0, v4
	v_max_f32_e32 v5, 0, v5
	v_max_f32_e32 v6, 0, v6
	v_max_f32_e32 v7, 0, v7
	v_max_f32_e32 v0, 0, v0
	v_max_f32_e32 v1, 0, v1
	v_max_f32_e32 v2, 0, v2
	v_max_f32_e32 v3, 0, v3
	v_pk_mul_f32 v[4:5], v[4:5], v[4:5]
	v_pk_mul_f32 v[6:7], v[6:7], v[6:7]
	v_pk_mul_f32 v[0:1], v[0:1], v[0:1]
	v_pk_mul_f32 v[2:3], v[2:3], v[2:3]
	v_cvt_pk_bf16_f32 v4, v4, v5
	v_cvt_pk_bf16_f32 v5, v6, v7
	v_cvt_pk_bf16_f32 v6, v0, v1
	v_cvt_pk_bf16_f32 v7, v2, v3
	global_store_dwordx4 v184, v[4:7], s[22:23] offset:256
	s_add_u32 s22, s22, s46
	s_addc_u32 s23, s23, 0
	v_pk_fma_f32 v[124:125], v[124:125], v[148:149], v[140:141] op_sel_hi:[1,0,1]
	v_pk_fma_f32 v[126:127], v[126:127], v[148:149], v[142:143] op_sel_hi:[1,0,1]
	v_pk_fma_f32 v[120:121], v[120:121], v[148:149], v[136:137] op_sel_hi:[1,0,1]
	v_pk_fma_f32 v[122:123], v[122:123], v[148:149], v[138:139] op_sel_hi:[1,0,1]
	v_max_f32_e32 v124, 0, v124
	v_max_f32_e32 v125, 0, v125
	v_max_f32_e32 v126, 0, v126
	v_max_f32_e32 v127, 0, v127
	v_max_f32_e32 v120, 0, v120
	v_max_f32_e32 v121, 0, v121
	v_max_f32_e32 v122, 0, v122
	v_max_f32_e32 v123, 0, v123
	v_pk_mul_f32 v[124:125], v[124:125], v[124:125]
	v_pk_mul_f32 v[126:127], v[126:127], v[126:127]
	v_pk_mul_f32 v[120:121], v[120:121], v[120:121]
	v_pk_mul_f32 v[122:123], v[122:123], v[122:123]
	v_cvt_pk_bf16_f32 v124, v124, v125
	v_cvt_pk_bf16_f32 v125, v126, v127
	v_cvt_pk_bf16_f32 v126, v120, v121
	v_cvt_pk_bf16_f32 v127, v122, v123
	global_store_dwordx4 v184, v[124:127], s[22:23]
	v_pk_fma_f32 v[116:117], v[116:117], v[148:149], v[132:133] op_sel_hi:[1,0,1]
	v_pk_fma_f32 v[118:119], v[118:119], v[148:149], v[134:135] op_sel_hi:[1,0,1]
	v_pk_fma_f32 v[112:113], v[112:113], v[148:149], v[128:129] op_sel_hi:[1,0,1]
	v_pk_fma_f32 v[114:115], v[114:115], v[148:149], v[130:131] op_sel_hi:[1,0,1]
	v_max_f32_e32 v116, 0, v116
	v_max_f32_e32 v117, 0, v117
	v_max_f32_e32 v118, 0, v118
	v_max_f32_e32 v119, 0, v119
	v_max_f32_e32 v112, 0, v112
	v_max_f32_e32 v113, 0, v113
	v_max_f32_e32 v114, 0, v114
	v_max_f32_e32 v115, 0, v115
	v_pk_mul_f32 v[116:117], v[116:117], v[116:117]
	v_pk_mul_f32 v[118:119], v[118:119], v[118:119]
	v_pk_mul_f32 v[112:113], v[112:113], v[112:113]
	v_pk_mul_f32 v[114:115], v[114:115], v[114:115]
	v_cvt_pk_bf16_f32 v116, v116, v117
	v_cvt_pk_bf16_f32 v117, v118, v119
	v_cvt_pk_bf16_f32 v118, v112, v113
	v_cvt_pk_bf16_f32 v119, v114, v115
	global_store_dwordx4 v184, v[116:119], s[22:23] offset:256
	s_add_u32 s22, s22, s46
	s_addc_u32 s23, s23, 0
	v_pk_fma_f32 v[108:109], v[108:109], v[150:151], v[140:141] op_sel_hi:[1,0,1]
	v_pk_fma_f32 v[110:111], v[110:111], v[150:151], v[142:143] op_sel_hi:[1,0,1]
	v_pk_fma_f32 v[104:105], v[104:105], v[150:151], v[136:137] op_sel_hi:[1,0,1]
	v_pk_fma_f32 v[106:107], v[106:107], v[150:151], v[138:139] op_sel_hi:[1,0,1]
	v_max_f32_e32 v108, 0, v108
	v_max_f32_e32 v109, 0, v109
	v_max_f32_e32 v110, 0, v110
	v_max_f32_e32 v111, 0, v111
	v_max_f32_e32 v104, 0, v104
	v_max_f32_e32 v105, 0, v105
	v_max_f32_e32 v106, 0, v106
	v_max_f32_e32 v107, 0, v107
	v_pk_mul_f32 v[108:109], v[108:109], v[108:109]
	v_pk_mul_f32 v[110:111], v[110:111], v[110:111]
	v_pk_mul_f32 v[104:105], v[104:105], v[104:105]
	v_pk_mul_f32 v[106:107], v[106:107], v[106:107]
	v_cvt_pk_bf16_f32 v108, v108, v109
	v_cvt_pk_bf16_f32 v109, v110, v111
	v_cvt_pk_bf16_f32 v110, v104, v105
	v_cvt_pk_bf16_f32 v111, v106, v107
	global_store_dwordx4 v184, v[108:111], s[22:23]
	v_pk_fma_f32 v[100:101], v[100:101], v[150:151], v[132:133] op_sel_hi:[1,0,1]
	v_pk_fma_f32 v[102:103], v[102:103], v[150:151], v[134:135] op_sel_hi:[1,0,1]
	v_pk_fma_f32 v[96:97], v[96:97], v[150:151], v[128:129] op_sel_hi:[1,0,1]
	v_pk_fma_f32 v[98:99], v[98:99], v[150:151], v[130:131] op_sel_hi:[1,0,1]
	v_max_f32_e32 v100, 0, v100
	v_max_f32_e32 v101, 0, v101
	v_max_f32_e32 v102, 0, v102
	v_max_f32_e32 v103, 0, v103
	v_max_f32_e32 v96, 0, v96
	v_max_f32_e32 v97, 0, v97
	v_max_f32_e32 v98, 0, v98
	v_max_f32_e32 v99, 0, v99
	v_pk_mul_f32 v[100:101], v[100:101], v[100:101]
	v_pk_mul_f32 v[102:103], v[102:103], v[102:103]
	v_pk_mul_f32 v[96:97], v[96:97], v[96:97]
	v_pk_mul_f32 v[98:99], v[98:99], v[98:99]
	v_cvt_pk_bf16_f32 v100, v100, v101
	v_cvt_pk_bf16_f32 v101, v102, v103
	v_cvt_pk_bf16_f32 v102, v96, v97
	v_cvt_pk_bf16_f32 v103, v98, v99
	global_store_dwordx4 v184, v[100:103], s[22:23] offset:256
	s_add_u32 s22, s22, s46
	s_addc_u32 s23, s23, 0
	s_add_u32 s22, s22, s46
	s_addc_u32 s23, s23, 0
	s_add_u32 s22, s22, s46
	s_addc_u32 s23, s23, 0
	s_add_u32 s22, s22, s46
	s_addc_u32 s23, s23, 0
	s_add_u32 s22, s22, s46
	s_addc_u32 s23, s23, 0
	v_pk_fma_f32 v[92:93], v[92:93], v[176:177], v[140:141] op_sel_hi:[1,0,1]
	v_pk_fma_f32 v[94:95], v[94:95], v[176:177], v[142:143] op_sel_hi:[1,0,1]
	v_pk_fma_f32 v[88:89], v[88:89], v[176:177], v[136:137] op_sel_hi:[1,0,1]
	v_pk_fma_f32 v[90:91], v[90:91], v[176:177], v[138:139] op_sel_hi:[1,0,1]
	v_max_f32_e32 v92, 0, v92
	v_max_f32_e32 v93, 0, v93
	v_max_f32_e32 v94, 0, v94
	v_max_f32_e32 v95, 0, v95
	v_max_f32_e32 v88, 0, v88
	v_max_f32_e32 v89, 0, v89
	v_max_f32_e32 v90, 0, v90
	v_max_f32_e32 v91, 0, v91
	v_pk_mul_f32 v[92:93], v[92:93], v[92:93]
	v_pk_mul_f32 v[94:95], v[94:95], v[94:95]
	v_pk_mul_f32 v[88:89], v[88:89], v[88:89]
	v_pk_mul_f32 v[90:91], v[90:91], v[90:91]
	v_cvt_pk_bf16_f32 v92, v92, v93
	v_cvt_pk_bf16_f32 v93, v94, v95
	v_cvt_pk_bf16_f32 v94, v88, v89
	v_cvt_pk_bf16_f32 v95, v90, v91
	global_store_dwordx4 v184, v[92:95], s[22:23]
	v_pk_fma_f32 v[84:85], v[84:85], v[176:177], v[132:133] op_sel_hi:[1,0,1]
	v_pk_fma_f32 v[86:87], v[86:87], v[176:177], v[134:135] op_sel_hi:[1,0,1]
	v_pk_fma_f32 v[80:81], v[80:81], v[176:177], v[128:129] op_sel_hi:[1,0,1]
	v_pk_fma_f32 v[82:83], v[82:83], v[176:177], v[130:131] op_sel_hi:[1,0,1]
	v_max_f32_e32 v84, 0, v84
	v_max_f32_e32 v85, 0, v85
	v_max_f32_e32 v86, 0, v86
	v_max_f32_e32 v87, 0, v87
	v_max_f32_e32 v80, 0, v80
	v_max_f32_e32 v81, 0, v81
	v_max_f32_e32 v82, 0, v82
	v_max_f32_e32 v83, 0, v83
	v_pk_mul_f32 v[84:85], v[84:85], v[84:85]
	v_pk_mul_f32 v[86:87], v[86:87], v[86:87]
	v_pk_mul_f32 v[80:81], v[80:81], v[80:81]
	v_pk_mul_f32 v[82:83], v[82:83], v[82:83]
	v_cvt_pk_bf16_f32 v84, v84, v85
	v_cvt_pk_bf16_f32 v85, v86, v87
	v_cvt_pk_bf16_f32 v86, v80, v81
	v_cvt_pk_bf16_f32 v87, v82, v83
	global_store_dwordx4 v184, v[84:87], s[22:23] offset:256
	s_add_u32 s22, s22, s46
	s_addc_u32 s23, s23, 0
	v_pk_fma_f32 v[76:77], v[76:77], v[178:179], v[140:141] op_sel_hi:[1,0,1]
	v_pk_fma_f32 v[78:79], v[78:79], v[178:179], v[142:143] op_sel_hi:[1,0,1]
	v_pk_fma_f32 v[72:73], v[72:73], v[178:179], v[136:137] op_sel_hi:[1,0,1]
	v_pk_fma_f32 v[74:75], v[74:75], v[178:179], v[138:139] op_sel_hi:[1,0,1]
	v_max_f32_e32 v76, 0, v76
	v_max_f32_e32 v77, 0, v77
	v_max_f32_e32 v78, 0, v78
	v_max_f32_e32 v79, 0, v79
	v_max_f32_e32 v72, 0, v72
	v_max_f32_e32 v73, 0, v73
	v_max_f32_e32 v74, 0, v74
	v_max_f32_e32 v75, 0, v75
	v_pk_mul_f32 v[76:77], v[76:77], v[76:77]
	v_pk_mul_f32 v[78:79], v[78:79], v[78:79]
	v_pk_mul_f32 v[72:73], v[72:73], v[72:73]
	v_pk_mul_f32 v[74:75], v[74:75], v[74:75]
	v_cvt_pk_bf16_f32 v76, v76, v77
	v_cvt_pk_bf16_f32 v77, v78, v79
	v_cvt_pk_bf16_f32 v78, v72, v73
	v_cvt_pk_bf16_f32 v79, v74, v75
	global_store_dwordx4 v184, v[76:79], s[22:23]
	v_pk_fma_f32 v[68:69], v[68:69], v[178:179], v[132:133] op_sel_hi:[1,0,1]
	v_pk_fma_f32 v[70:71], v[70:71], v[178:179], v[134:135] op_sel_hi:[1,0,1]
	v_pk_fma_f32 v[64:65], v[64:65], v[178:179], v[128:129] op_sel_hi:[1,0,1]
	v_pk_fma_f32 v[66:67], v[66:67], v[178:179], v[130:131] op_sel_hi:[1,0,1]
	v_max_f32_e32 v68, 0, v68
	v_max_f32_e32 v69, 0, v69
	v_max_f32_e32 v70, 0, v70
	v_max_f32_e32 v71, 0, v71
	v_max_f32_e32 v64, 0, v64
	v_max_f32_e32 v65, 0, v65
	v_max_f32_e32 v66, 0, v66
	v_max_f32_e32 v67, 0, v67
	v_pk_mul_f32 v[68:69], v[68:69], v[68:69]
	v_pk_mul_f32 v[70:71], v[70:71], v[70:71]
	v_pk_mul_f32 v[64:65], v[64:65], v[64:65]
	v_pk_mul_f32 v[66:67], v[66:67], v[66:67]
	v_cvt_pk_bf16_f32 v68, v68, v69
	v_cvt_pk_bf16_f32 v69, v70, v71
	v_cvt_pk_bf16_f32 v70, v64, v65
	v_cvt_pk_bf16_f32 v71, v66, v67
	global_store_dwordx4 v184, v[68:71], s[22:23] offset:256
	s_add_u32 s22, s22, s46
	s_addc_u32 s23, s23, 0
	v_pk_fma_f32 v[60:61], v[60:61], v[180:181], v[140:141] op_sel_hi:[1,0,1]
	v_pk_fma_f32 v[62:63], v[62:63], v[180:181], v[142:143] op_sel_hi:[1,0,1]
	v_pk_fma_f32 v[56:57], v[56:57], v[180:181], v[136:137] op_sel_hi:[1,0,1]
	v_pk_fma_f32 v[58:59], v[58:59], v[180:181], v[138:139] op_sel_hi:[1,0,1]
	v_max_f32_e32 v60, 0, v60
	v_max_f32_e32 v61, 0, v61
	v_max_f32_e32 v62, 0, v62
	v_max_f32_e32 v63, 0, v63
	v_max_f32_e32 v56, 0, v56
	v_max_f32_e32 v57, 0, v57
	v_max_f32_e32 v58, 0, v58
	v_max_f32_e32 v59, 0, v59
	v_pk_mul_f32 v[60:61], v[60:61], v[60:61]
	v_pk_mul_f32 v[62:63], v[62:63], v[62:63]
	v_pk_mul_f32 v[56:57], v[56:57], v[56:57]
	v_pk_mul_f32 v[58:59], v[58:59], v[58:59]
	v_cvt_pk_bf16_f32 v60, v60, v61
	v_cvt_pk_bf16_f32 v61, v62, v63
	v_cvt_pk_bf16_f32 v62, v56, v57
	v_cvt_pk_bf16_f32 v63, v58, v59
	global_store_dwordx4 v184, v[60:63], s[22:23]
	v_pk_fma_f32 v[52:53], v[52:53], v[180:181], v[132:133] op_sel_hi:[1,0,1]
	v_pk_fma_f32 v[54:55], v[54:55], v[180:181], v[134:135] op_sel_hi:[1,0,1]
	v_pk_fma_f32 v[48:49], v[48:49], v[180:181], v[128:129] op_sel_hi:[1,0,1]
	v_pk_fma_f32 v[50:51], v[50:51], v[180:181], v[130:131] op_sel_hi:[1,0,1]
	v_max_f32_e32 v52, 0, v52
	v_max_f32_e32 v53, 0, v53
	v_max_f32_e32 v54, 0, v54
	v_max_f32_e32 v55, 0, v55
	v_max_f32_e32 v48, 0, v48
	v_max_f32_e32 v49, 0, v49
	v_max_f32_e32 v50, 0, v50
	v_max_f32_e32 v51, 0, v51
	v_pk_mul_f32 v[52:53], v[52:53], v[52:53]
	v_pk_mul_f32 v[54:55], v[54:55], v[54:55]
	v_pk_mul_f32 v[48:49], v[48:49], v[48:49]
	v_pk_mul_f32 v[50:51], v[50:51], v[50:51]
	v_cvt_pk_bf16_f32 v52, v52, v53
	v_cvt_pk_bf16_f32 v53, v54, v55
	v_cvt_pk_bf16_f32 v54, v48, v49
	v_cvt_pk_bf16_f32 v55, v50, v51
	global_store_dwordx4 v184, v[52:55], s[22:23] offset:256
	s_add_u32 s22, s22, s46
	s_addc_u32 s23, s23, 0
	v_pk_fma_f32 v[44:45], v[44:45], v[182:183], v[140:141] op_sel_hi:[1,0,1]
	v_pk_fma_f32 v[46:47], v[46:47], v[182:183], v[142:143] op_sel_hi:[1,0,1]
	v_pk_fma_f32 v[40:41], v[40:41], v[182:183], v[136:137] op_sel_hi:[1,0,1]
	v_pk_fma_f32 v[42:43], v[42:43], v[182:183], v[138:139] op_sel_hi:[1,0,1]
	v_max_f32_e32 v44, 0, v44
	v_max_f32_e32 v45, 0, v45
	v_max_f32_e32 v46, 0, v46
	v_max_f32_e32 v47, 0, v47
	v_max_f32_e32 v40, 0, v40
	v_max_f32_e32 v41, 0, v41
	v_max_f32_e32 v42, 0, v42
	v_max_f32_e32 v43, 0, v43
	v_pk_mul_f32 v[44:45], v[44:45], v[44:45]
	v_pk_mul_f32 v[46:47], v[46:47], v[46:47]
	v_pk_mul_f32 v[40:41], v[40:41], v[40:41]
	v_pk_mul_f32 v[42:43], v[42:43], v[42:43]
	v_cvt_pk_bf16_f32 v44, v44, v45
	v_cvt_pk_bf16_f32 v45, v46, v47
	v_cvt_pk_bf16_f32 v46, v40, v41
	v_cvt_pk_bf16_f32 v47, v42, v43
	global_store_dwordx4 v184, v[44:47], s[22:23]
	v_pk_fma_f32 v[36:37], v[36:37], v[182:183], v[132:133] op_sel_hi:[1,0,1]
	v_pk_fma_f32 v[38:39], v[38:39], v[182:183], v[134:135] op_sel_hi:[1,0,1]
	v_pk_fma_f32 v[32:33], v[32:33], v[182:183], v[128:129] op_sel_hi:[1,0,1]
	v_pk_fma_f32 v[34:35], v[34:35], v[182:183], v[130:131] op_sel_hi:[1,0,1]
	v_max_f32_e32 v36, 0, v36
	v_max_f32_e32 v37, 0, v37
	v_max_f32_e32 v38, 0, v38
	v_max_f32_e32 v39, 0, v39
	v_max_f32_e32 v32, 0, v32
	v_max_f32_e32 v33, 0, v33
	v_max_f32_e32 v34, 0, v34
	v_max_f32_e32 v35, 0, v35
	v_pk_mul_f32 v[36:37], v[36:37], v[36:37]
	v_pk_mul_f32 v[38:39], v[38:39], v[38:39]
	v_pk_mul_f32 v[32:33], v[32:33], v[32:33]
	v_pk_mul_f32 v[34:35], v[34:35], v[34:35]
	v_cvt_pk_bf16_f32 v36, v36, v37
	v_cvt_pk_bf16_f32 v37, v38, v39
	v_cvt_pk_bf16_f32 v38, v32, v33
	v_cvt_pk_bf16_f32 v39, v34, v35
	global_store_dwordx4 v184, v[36:39], s[22:23] offset:256
	s_branch .LBB0_461

.LBB0_407:
	v_cndmask_b32_e64 v144, 0, 1, s[60:61]
	s_waitcnt lgkmcnt(0)
	v_pk_fma_f32 v[176:177], v[18:19], v[148:149], v[142:143] op_sel_hi:[1,0,1]
	v_pk_fma_f32 v[178:179], v[16:17], v[148:149], v[140:141] op_sel_hi:[1,0,1]
	v_pk_fma_f32 v[180:181], v[30:31], v[148:149], v[138:139] op_sel_hi:[1,0,1]
	v_cmp_ne_u32_e64 s[44:45], 1, v144
	s_andn2_b64 vcc, exec, s[60:61]
	v_pk_fma_f32 v[182:183], v[28:29], v[148:149], v[136:137] op_sel_hi:[1,0,1]
	s_cbranch_vccnz .LBB0_409
	v_max_f32_e32 v151, 0, v183
	v_max_f32_e32 v150, 0, v182
	v_max_f32_e32 v145, 0, v179
	v_max_f32_e32 v147, 0, v177
	v_max_f32_e32 v181, 0, v181
	v_max_f32_e32 v144, 0, v178
	v_max_f32_e32 v146, 0, v176
	v_max_f32_e32 v180, 0, v180
	v_pk_mul_f32 v[176:177], v[146:147], v[146:147]
	v_pk_mul_f32 v[178:179], v[144:145], v[144:145]
	v_pk_mul_f32 v[180:181], v[180:181], v[180:181]
	v_pk_mul_f32 v[182:183], v[150:151], v[150:151]
.LBB0_409:
	s_cmp_lt_i32 s56, s95
	v_mov_b32_e32 v144, s81
	s_cselect_b64 vcc, -1, 0
	v_cndmask_b32_e32 v144, 1.0, v144, vcc
	v_lshl_or_b32 v146, s56, 8, v228
	v_mad_i64_i32 v[150:151], s[22:23], v174, s10, 0
	v_ashrrev_i32_e32 v147, 31, v146
	v_lshl_add_u64 v[150:151], v[150:151], 1, s[78:79]
	v_pk_mul_f32 v[184:185], v[144:145], v[176:177] op_sel_hi:[0,1]
	v_pk_mul_f32 v[176:177], v[144:145], v[178:179] op_sel_hi:[0,1]
	v_pk_mul_f32 v[180:181], v[144:145], v[180:181] op_sel_hi:[0,1]
	v_pk_mul_f32 v[178:179], v[144:145], v[182:183] op_sel_hi:[0,1]
	v_mov_b32_e32 v149, v148
	v_lshl_add_u64 v[150:151], v[146:147], 1, v[150:151]
	v_cvt_pk_bf16_f32 v176, v176, v177
	v_cvt_pk_bf16_f32 v177, v184, v185
	v_cvt_pk_bf16_f32 v178, v178, v179
	v_cvt_pk_bf16_f32 v179, v180, v181
	v_mov_b32_e32 v180, v148
	v_mov_b32_e32 v181, v148
	global_store_dwordx4 v[150:151], v[176:179], off
	s_and_b64 vcc, exec, s[44:45]
	s_nop 0
	v_pk_fma_f32 v[176:177], v[26:27], v[180:181], v[134:135]
	v_pk_fma_f32 v[178:179], v[24:25], v[148:149], v[132:133]
	v_pk_fma_f32 v[180:181], v[22:23], v[180:181], v[130:131]
	v_pk_fma_f32 v[148:149], v[20:21], v[148:149], v[128:129]
	s_cbranch_vccnz .LBB0_411
	v_max_f32_e32 v179, 0, v179
	v_max_f32_e32 v178, 0, v178
	v_max_f32_e32 v177, 0, v177
	v_max_f32_e32 v176, 0, v176
	v_max_f32_e32 v149, 0, v149
	v_max_f32_e32 v148, 0, v148
	v_max_f32_e32 v181, 0, v181
	v_max_f32_e32 v180, 0, v180
	v_pk_mul_f32 v[176:177], v[176:177], v[176:177]
	v_pk_mul_f32 v[178:179], v[178:179], v[178:179]
	v_pk_mul_f32 v[180:181], v[180:181], v[180:181]
	v_pk_mul_f32 v[148:149], v[148:149], v[148:149]

.LBB0_414:
	v_pk_fma_f32 v[178:179], v[14:15], v[148:149], v[142:143] op_sel_hi:[1,0,1]
	v_pk_fma_f32 v[180:181], v[12:13], v[148:149], v[140:141] op_sel_hi:[1,0,1]
	v_pk_fma_f32 v[182:183], v[10:11], v[148:149], v[138:139] op_sel_hi:[1,0,1]
	s_and_b64 vcc, exec, s[44:45]
	v_pk_fma_f32 v[184:185], v[8:9], v[148:149], v[136:137] op_sel_hi:[1,0,1]
	s_cbranch_vccnz .LBB0_416
	v_max_f32_e32 v151, 0, v181
	v_max_f32_e32 v150, 0, v180
	v_max_f32_e32 v177, 0, v179
	v_max_f32_e32 v176, 0, v178
	v_max_f32_e32 v185, 0, v185
	v_max_f32_e32 v184, 0, v184
	v_max_f32_e32 v183, 0, v183
	v_max_f32_e32 v182, 0, v182
	v_pk_mul_f32 v[178:179], v[176:177], v[176:177]
	v_pk_mul_f32 v[180:181], v[150:151], v[150:151]
	v_pk_mul_f32 v[182:183], v[182:183], v[182:183]
	v_pk_mul_f32 v[184:185], v[184:185], v[184:185]
.LBB0_416:
	v_or_b32_e32 v150, 16, v174
	v_mad_i64_i32 v[150:151], s[22:23], v150, s10, 0
	v_mov_b32_e32 v176, v144
	v_mov_b32_e32 v177, v144
	v_lshl_add_u64 v[150:151], v[150:151], 1, s[78:79]
	v_pk_mul_f32 v[186:187], v[176:177], v[178:179]
	v_pk_mul_f32 v[178:179], v[144:145], v[180:181]
	v_pk_mul_f32 v[182:183], v[176:177], v[182:183]
	v_pk_mul_f32 v[180:181], v[144:145], v[184:185]
	v_mov_b32_e32 v149, v148
	v_lshl_add_u64 v[150:151], v[146:147], 1, v[150:151]
	v_cvt_pk_bf16_f32 v178, v178, v179
	v_cvt_pk_bf16_f32 v179, v186, v187
	v_cvt_pk_bf16_f32 v180, v180, v181
	v_cvt_pk_bf16_f32 v181, v182, v183
	v_mov_b32_e32 v182, v148
	v_mov_b32_e32 v183, v148
	global_store_dwordx4 v[150:151], v[178:181], off
	s_and_b64 vcc, exec, s[44:45]
	s_nop 0
	v_pk_fma_f32 v[178:179], v[6:7], v[182:183], v[134:135]
	v_pk_fma_f32 v[180:181], v[4:5], v[148:149], v[132:133]
	v_pk_fma_f32 v[182:183], v[2:3], v[182:183], v[130:131]
	v_pk_fma_f32 v[148:149], v[0:1], v[148:149], v[128:129]
	s_cbranch_vccnz .LBB0_418
	v_max_f32_e32 v181, 0, v181
	v_max_f32_e32 v180, 0, v180
	v_max_f32_e32 v179, 0, v179
	v_max_f32_e32 v178, 0, v178
	v_max_f32_e32 v183, 0, v183
	v_max_f32_e32 v149, 0, v149
	v_max_f32_e32 v148, 0, v148
	v_max_f32_e32 v182, 0, v182
	v_pk_mul_f32 v[178:179], v[178:179], v[178:179]
	v_pk_mul_f32 v[180:181], v[180:181], v[180:181]
	v_pk_mul_f32 v[182:183], v[182:183], v[182:183]
	v_pk_mul_f32 v[148:149], v[148:149], v[148:149]

.LBB0_421:
	v_pk_fma_f32 v[126:127], v[126:127], v[148:149], v[142:143] op_sel_hi:[1,0,1]
	v_pk_fma_f32 v[124:125], v[124:125], v[148:149], v[140:141] op_sel_hi:[1,0,1]
	v_pk_fma_f32 v[150:151], v[122:123], v[148:149], v[138:139] op_sel_hi:[1,0,1]
	s_and_b64 vcc, exec, s[44:45]
	v_pk_fma_f32 v[176:177], v[120:121], v[148:149], v[136:137] op_sel_hi:[1,0,1]
	s_cbranch_vccnz .LBB0_423
	v_max_f32_e32 v121, 0, v125
	v_max_f32_e32 v120, v124, v124
	v_max_f32_e32 v177, 0, v177
	v_max_f32_e32 v176, 0, v176
	v_max_f32_e32 v123, 0, v127
	v_max_f32_e32 v151, 0, v151
	v_max_f32_e32 v120, 0, v120
	v_max_f32_e32 v122, 0, v126
	v_max_f32_e32 v150, 0, v150
	v_pk_mul_f32 v[126:127], v[122:123], v[122:123]
	v_pk_mul_f32 v[124:125], v[120:121], v[120:121]
	v_pk_mul_f32 v[150:151], v[150:151], v[150:151]
	v_pk_mul_f32 v[176:177], v[176:177], v[176:177]
.LBB0_423:
	v_or_b32_e32 v120, 32, v174
	v_mad_i64_i32 v[120:121], s[22:23], v120, s10, 0
	v_lshl_add_u64 v[120:121], v[120:121], 1, s[78:79]
	v_mov_b32_e32 v122, v144
	v_mov_b32_e32 v123, v144
	v_pk_mul_f32 v[124:125], v[144:145], v[124:125]
	v_lshl_add_u64 v[120:121], v[146:147], 1, v[120:121]
	v_pk_mul_f32 v[126:127], v[122:123], v[126:127]
	v_cvt_pk_bf16_f32 v124, v124, v125
	v_mov_b32_e32 v149, v148
	v_cvt_pk_bf16_f32 v125, v126, v127
	v_pk_mul_f32 v[150:151], v[122:123], v[150:151]
	v_pk_mul_f32 v[176:177], v[144:145], v[176:177]
	v_pk_fma_f32 v[116:117], v[116:117], v[148:149], v[132:133]
	v_cvt_pk_bf16_f32 v126, v176, v177
	v_cvt_pk_bf16_f32 v127, v150, v151
	global_store_dwordx4 v[120:121], v[124:127], off
	s_and_b64 vcc, exec, s[44:45]
	v_pk_fma_f32 v[112:113], v[112:113], v[148:149], v[128:129]
	v_mov_b32_e32 v124, v148
	v_mov_b32_e32 v125, v148
	v_pk_fma_f32 v[118:119], v[118:119], v[124:125], v[134:135]
	v_pk_fma_f32 v[114:115], v[114:115], v[124:125], v[130:131]
	s_cbranch_vccnz .LBB0_425
	v_max_f32_e32 v117, 0, v117
	v_max_f32_e32 v116, 0, v116
	v_max_f32_e32 v119, 0, v119
	v_max_f32_e32 v118, 0, v118
	v_max_f32_e32 v113, 0, v113
	v_max_f32_e32 v112, 0, v112
	v_max_f32_e32 v115, 0, v115
	v_max_f32_e32 v114, 0, v114
	v_pk_mul_f32 v[118:119], v[118:119], v[118:119]
	v_pk_mul_f32 v[116:117], v[116:117], v[116:117]
	v_pk_mul_f32 v[114:115], v[114:115], v[114:115]
	v_pk_mul_f32 v[112:113], v[112:113], v[112:113]

.LBB0_428:
	v_pk_fma_f32 v[110:111], v[110:111], v[112:113], v[142:143] op_sel_hi:[1,0,1]
	v_pk_fma_f32 v[108:109], v[108:109], v[112:113], v[140:141] op_sel_hi:[1,0,1]
	v_pk_fma_f32 v[114:115], v[106:107], v[112:113], v[138:139] op_sel_hi:[1,0,1]
	s_and_b64 vcc, exec, s[44:45]
	v_pk_fma_f32 v[116:117], v[104:105], v[112:113], v[136:137] op_sel_hi:[1,0,1]
	s_cbranch_vccnz .LBB0_430
	v_max_f32_e32 v105, 0, v109
	v_max_f32_e32 v104, v108, v108
	v_max_f32_e32 v117, 0, v117
	v_max_f32_e32 v116, 0, v116
	v_max_f32_e32 v107, 0, v111
	v_max_f32_e32 v115, 0, v115
	v_max_f32_e32 v104, 0, v104
	v_max_f32_e32 v106, 0, v110
	v_max_f32_e32 v114, 0, v114
	v_pk_mul_f32 v[110:111], v[106:107], v[106:107]
	v_pk_mul_f32 v[108:109], v[104:105], v[104:105]
	v_pk_mul_f32 v[114:115], v[114:115], v[114:115]
	v_pk_mul_f32 v[116:117], v[116:117], v[116:117]
.LBB0_430:
	v_or_b32_e32 v104, 48, v174
	v_mad_i64_i32 v[104:105], s[22:23], v104, s10, 0
	v_lshl_add_u64 v[104:105], v[104:105], 1, s[78:79]
	v_mov_b32_e32 v106, v144
	v_mov_b32_e32 v107, v144
	v_pk_mul_f32 v[108:109], v[144:145], v[108:109]
	v_lshl_add_u64 v[104:105], v[146:147], 1, v[104:105]
	v_pk_mul_f32 v[110:111], v[106:107], v[110:111]
	v_cvt_pk_bf16_f32 v108, v108, v109
	v_mov_b32_e32 v113, v112
	v_cvt_pk_bf16_f32 v109, v110, v111
	v_pk_mul_f32 v[114:115], v[106:107], v[114:115]
	v_pk_mul_f32 v[116:117], v[144:145], v[116:117]
	v_pk_fma_f32 v[100:101], v[100:101], v[112:113], v[132:133]
	v_cvt_pk_bf16_f32 v110, v116, v117
	v_cvt_pk_bf16_f32 v111, v114, v115
	global_store_dwordx4 v[104:105], v[108:111], off
	s_and_b64 vcc, exec, s[44:45]
	v_pk_fma_f32 v[96:97], v[96:97], v[112:113], v[128:129]
	v_mov_b32_e32 v108, v112
	v_mov_b32_e32 v109, v112
	v_pk_fma_f32 v[102:103], v[102:103], v[108:109], v[134:135]
	v_pk_fma_f32 v[98:99], v[98:99], v[108:109], v[130:131]
	s_cbranch_vccnz .LBB0_432
	v_max_f32_e32 v101, 0, v101
	v_max_f32_e32 v100, 0, v100
	v_max_f32_e32 v103, 0, v103
	v_max_f32_e32 v102, 0, v102
	v_max_f32_e32 v97, 0, v97
	v_max_f32_e32 v96, 0, v96
	v_max_f32_e32 v99, 0, v99
	v_max_f32_e32 v98, 0, v98
	v_pk_mul_f32 v[102:103], v[102:103], v[102:103]
	v_pk_mul_f32 v[100:101], v[100:101], v[100:101]
	v_pk_mul_f32 v[98:99], v[98:99], v[98:99]
	v_pk_mul_f32 v[96:97], v[96:97], v[96:97]

.LBB0_435:
	v_pk_fma_f32 v[94:95], v[94:95], v[96:97], v[142:143] op_sel_hi:[1,0,1]
	v_pk_fma_f32 v[92:93], v[92:93], v[96:97], v[140:141] op_sel_hi:[1,0,1]
	v_pk_fma_f32 v[98:99], v[90:91], v[96:97], v[138:139] op_sel_hi:[1,0,1]
	s_and_b64 vcc, exec, s[44:45]
	v_pk_fma_f32 v[100:101], v[88:89], v[96:97], v[136:137] op_sel_hi:[1,0,1]
	s_cbranch_vccnz .LBB0_437
	v_max_f32_e32 v89, 0, v93
	v_max_f32_e32 v88, v92, v92
	v_max_f32_e32 v101, 0, v101
	v_max_f32_e32 v100, 0, v100
	v_max_f32_e32 v91, 0, v95
	v_max_f32_e32 v99, 0, v99
	v_max_f32_e32 v88, 0, v88
	v_max_f32_e32 v90, 0, v94
	v_max_f32_e32 v98, 0, v98
	v_pk_mul_f32 v[94:95], v[90:91], v[90:91]
	v_pk_mul_f32 v[92:93], v[88:89], v[88:89]
	v_pk_mul_f32 v[98:99], v[98:99], v[98:99]
	v_pk_mul_f32 v[100:101], v[100:101], v[100:101]
.LBB0_437:
	v_add_u32_e32 v88, 0x80, v174
	v_mad_i64_i32 v[88:89], s[22:23], v88, s10, 0
	v_lshl_add_u64 v[88:89], v[88:89], 1, s[78:79]
	v_mov_b32_e32 v90, v144
	v_mov_b32_e32 v91, v144
	v_pk_mul_f32 v[92:93], v[144:145], v[92:93]
	v_lshl_add_u64 v[88:89], v[146:147], 1, v[88:89]
	v_pk_mul_f32 v[94:95], v[90:91], v[94:95]
	v_cvt_pk_bf16_f32 v92, v92, v93
	v_mov_b32_e32 v97, v96
	v_cvt_pk_bf16_f32 v93, v94, v95
	v_pk_mul_f32 v[98:99], v[90:91], v[98:99]
	v_pk_mul_f32 v[100:101], v[144:145], v[100:101]
	v_pk_fma_f32 v[84:85], v[84:85], v[96:97], v[132:133]
	v_cvt_pk_bf16_f32 v94, v100, v101
	v_cvt_pk_bf16_f32 v95, v98, v99
	global_store_dwordx4 v[88:89], v[92:95], off
	s_and_b64 vcc, exec, s[44:45]
	v_pk_fma_f32 v[80:81], v[80:81], v[96:97], v[128:129]
	v_mov_b32_e32 v92, v96
	v_mov_b32_e32 v93, v96
	v_pk_fma_f32 v[86:87], v[86:87], v[92:93], v[134:135]
	v_pk_fma_f32 v[82:83], v[82:83], v[92:93], v[130:131]
	s_cbranch_vccnz .LBB0_439
	v_max_f32_e32 v85, 0, v85
	v_max_f32_e32 v84, 0, v84
	v_max_f32_e32 v87, 0, v87
	v_max_f32_e32 v86, 0, v86
	v_max_f32_e32 v81, 0, v81
	v_max_f32_e32 v80, 0, v80
	v_max_f32_e32 v83, 0, v83
	v_max_f32_e32 v82, 0, v82
	v_pk_mul_f32 v[86:87], v[86:87], v[86:87]
	v_pk_mul_f32 v[84:85], v[84:85], v[84:85]
	v_pk_mul_f32 v[82:83], v[82:83], v[82:83]
	v_pk_mul_f32 v[80:81], v[80:81], v[80:81]

.LBB0_442:
	v_pk_fma_f32 v[78:79], v[78:79], v[80:81], v[142:143] op_sel_hi:[1,0,1]
	v_pk_fma_f32 v[76:77], v[76:77], v[80:81], v[140:141] op_sel_hi:[1,0,1]
	v_pk_fma_f32 v[82:83], v[74:75], v[80:81], v[138:139] op_sel_hi:[1,0,1]
	s_and_b64 vcc, exec, s[44:45]
	v_pk_fma_f32 v[84:85], v[72:73], v[80:81], v[136:137] op_sel_hi:[1,0,1]
	s_cbranch_vccnz .LBB0_444
	v_max_f32_e32 v73, 0, v77
	v_max_f32_e32 v72, v76, v76
	v_max_f32_e32 v85, 0, v85
	v_max_f32_e32 v84, 0, v84
	v_max_f32_e32 v75, 0, v79
	v_max_f32_e32 v83, 0, v83
	v_max_f32_e32 v72, 0, v72
	v_max_f32_e32 v74, 0, v78
	v_max_f32_e32 v82, 0, v82
	v_pk_mul_f32 v[78:79], v[74:75], v[74:75]
	v_pk_mul_f32 v[76:77], v[72:73], v[72:73]
	v_pk_mul_f32 v[82:83], v[82:83], v[82:83]
	v_pk_mul_f32 v[84:85], v[84:85], v[84:85]
.LBB0_444:
	v_add_u32_e32 v72, 0x90, v174
	v_mad_i64_i32 v[72:73], s[22:23], v72, s10, 0
	v_lshl_add_u64 v[72:73], v[72:73], 1, s[78:79]
	v_mov_b32_e32 v74, v144
	v_mov_b32_e32 v75, v144
	v_pk_mul_f32 v[76:77], v[144:145], v[76:77]
	v_lshl_add_u64 v[72:73], v[146:147], 1, v[72:73]
	v_pk_mul_f32 v[78:79], v[74:75], v[78:79]
	v_cvt_pk_bf16_f32 v76, v76, v77
	v_mov_b32_e32 v81, v80
	v_cvt_pk_bf16_f32 v77, v78, v79
	v_pk_mul_f32 v[82:83], v[74:75], v[82:83]
	v_pk_mul_f32 v[84:85], v[144:145], v[84:85]
	v_pk_fma_f32 v[68:69], v[68:69], v[80:81], v[132:133]
	v_cvt_pk_bf16_f32 v78, v84, v85
	v_cvt_pk_bf16_f32 v79, v82, v83
	global_store_dwordx4 v[72:73], v[76:79], off
	s_and_b64 vcc, exec, s[44:45]
	v_pk_fma_f32 v[64:65], v[64:65], v[80:81], v[128:129]
	v_mov_b32_e32 v76, v80
	v_mov_b32_e32 v77, v80
	v_pk_fma_f32 v[70:71], v[70:71], v[76:77], v[134:135]
	v_pk_fma_f32 v[66:67], v[66:67], v[76:77], v[130:131]
	s_cbranch_vccnz .LBB0_446
	v_max_f32_e32 v69, 0, v69
	v_max_f32_e32 v68, 0, v68
	v_max_f32_e32 v71, 0, v71
	v_max_f32_e32 v70, 0, v70
	v_max_f32_e32 v65, 0, v65
	v_max_f32_e32 v64, 0, v64
	v_max_f32_e32 v67, 0, v67
	v_max_f32_e32 v66, 0, v66
	v_pk_mul_f32 v[70:71], v[70:71], v[70:71]
	v_pk_mul_f32 v[68:69], v[68:69], v[68:69]
	v_pk_mul_f32 v[66:67], v[66:67], v[66:67]
	v_pk_mul_f32 v[64:65], v[64:65], v[64:65]

.LBB0_449:
	v_pk_fma_f32 v[62:63], v[62:63], v[64:65], v[142:143] op_sel_hi:[1,0,1]
	v_pk_fma_f32 v[60:61], v[60:61], v[64:65], v[140:141] op_sel_hi:[1,0,1]
	v_pk_fma_f32 v[66:67], v[58:59], v[64:65], v[138:139] op_sel_hi:[1,0,1]
	s_and_b64 vcc, exec, s[44:45]
	v_pk_fma_f32 v[68:69], v[56:57], v[64:65], v[136:137] op_sel_hi:[1,0,1]
	s_cbranch_vccnz .LBB0_451
	v_max_f32_e32 v57, 0, v61
	v_max_f32_e32 v56, v60, v60
	v_max_f32_e32 v69, 0, v69
	v_max_f32_e32 v68, 0, v68
	v_max_f32_e32 v59, 0, v63
	v_max_f32_e32 v67, 0, v67
	v_max_f32_e32 v56, 0, v56
	v_max_f32_e32 v58, 0, v62
	v_max_f32_e32 v66, 0, v66
	v_pk_mul_f32 v[62:63], v[58:59], v[58:59]
	v_pk_mul_f32 v[60:61], v[56:57], v[56:57]
	v_pk_mul_f32 v[66:67], v[66:67], v[66:67]
	v_pk_mul_f32 v[68:69], v[68:69], v[68:69]
.LBB0_451:
	v_add_u32_e32 v56, 0xa0, v174
	v_mad_i64_i32 v[56:57], s[22:23], v56, s10, 0
	v_lshl_add_u64 v[56:57], v[56:57], 1, s[78:79]
	v_mov_b32_e32 v58, v144
	v_mov_b32_e32 v59, v144
	v_pk_mul_f32 v[60:61], v[144:145], v[60:61]
	v_lshl_add_u64 v[56:57], v[146:147], 1, v[56:57]
	v_pk_mul_f32 v[62:63], v[58:59], v[62:63]
	v_cvt_pk_bf16_f32 v60, v60, v61
	v_mov_b32_e32 v65, v64
	v_cvt_pk_bf16_f32 v61, v62, v63
	v_pk_mul_f32 v[66:67], v[58:59], v[66:67]
	v_pk_mul_f32 v[68:69], v[144:145], v[68:69]
	v_pk_fma_f32 v[52:53], v[52:53], v[64:65], v[132:133]
	v_cvt_pk_bf16_f32 v62, v68, v69
	v_cvt_pk_bf16_f32 v63, v66, v67
	global_store_dwordx4 v[56:57], v[60:63], off
	s_and_b64 vcc, exec, s[44:45]
	v_pk_fma_f32 v[48:49], v[48:49], v[64:65], v[128:129]
	v_mov_b32_e32 v60, v64
	v_mov_b32_e32 v61, v64
	v_pk_fma_f32 v[54:55], v[54:55], v[60:61], v[134:135]
	v_pk_fma_f32 v[50:51], v[50:51], v[60:61], v[130:131]
	s_cbranch_vccnz .LBB0_453
	v_max_f32_e32 v53, 0, v53
	v_max_f32_e32 v52, 0, v52
	v_max_f32_e32 v55, 0, v55
	v_max_f32_e32 v54, 0, v54
	v_max_f32_e32 v49, 0, v49
	v_max_f32_e32 v48, 0, v48
	v_max_f32_e32 v51, 0, v51
	v_max_f32_e32 v50, 0, v50
	v_pk_mul_f32 v[54:55], v[54:55], v[54:55]
	v_pk_mul_f32 v[52:53], v[52:53], v[52:53]
	v_pk_mul_f32 v[50:51], v[50:51], v[50:51]
	v_pk_mul_f32 v[48:49], v[48:49], v[48:49]

.LBB0_456:
	v_pk_fma_f32 v[46:47], v[46:47], v[48:49], v[142:143] op_sel_hi:[1,0,1]
	v_pk_fma_f32 v[44:45], v[44:45], v[48:49], v[140:141] op_sel_hi:[1,0,1]
	v_pk_fma_f32 v[50:51], v[42:43], v[48:49], v[138:139] op_sel_hi:[1,0,1]
	s_and_b64 vcc, exec, s[44:45]
	v_pk_fma_f32 v[52:53], v[40:41], v[48:49], v[136:137] op_sel_hi:[1,0,1]
	s_cbranch_vccnz .LBB0_458
	v_max_f32_e32 v41, 0, v45
	v_max_f32_e32 v40, v44, v44
	v_max_f32_e32 v53, 0, v53
	v_max_f32_e32 v52, 0, v52
	v_max_f32_e32 v43, 0, v47
	v_max_f32_e32 v51, 0, v51
	v_max_f32_e32 v40, 0, v40
	v_max_f32_e32 v42, 0, v46
	v_max_f32_e32 v50, 0, v50
	v_pk_mul_f32 v[46:47], v[42:43], v[42:43]
	v_pk_mul_f32 v[44:45], v[40:41], v[40:41]
	v_pk_mul_f32 v[50:51], v[50:51], v[50:51]
	v_pk_mul_f32 v[52:53], v[52:53], v[52:53]
.LBB0_458:
	v_add_u32_e32 v40, 0xb0, v174
	v_mad_i64_i32 v[40:41], s[22:23], v40, s10, 0
	v_lshl_add_u64 v[40:41], v[40:41], 1, s[78:79]
	v_mov_b32_e32 v42, v144
	v_mov_b32_e32 v43, v144
	v_pk_mul_f32 v[44:45], v[144:145], v[44:45]
	v_lshl_add_u64 v[40:41], v[146:147], 1, v[40:41]
	v_pk_mul_f32 v[46:47], v[42:43], v[46:47]
	v_cvt_pk_bf16_f32 v44, v44, v45
	v_mov_b32_e32 v49, v48
	v_cvt_pk_bf16_f32 v45, v46, v47
	v_pk_mul_f32 v[50:51], v[42:43], v[50:51]
	v_pk_mul_f32 v[52:53], v[144:145], v[52:53]
	v_pk_fma_f32 v[36:37], v[36:37], v[48:49], v[132:133]
	v_cvt_pk_bf16_f32 v46, v52, v53
	v_cvt_pk_bf16_f32 v47, v50, v51
	global_store_dwordx4 v[40:41], v[44:47], off
	s_and_b64 vcc, exec, s[44:45]
	v_pk_fma_f32 v[32:33], v[32:33], v[48:49], v[128:129]
	v_mov_b32_e32 v44, v48
	v_mov_b32_e32 v45, v48
	v_pk_fma_f32 v[38:39], v[38:39], v[44:45], v[134:135]
	v_pk_fma_f32 v[34:35], v[34:35], v[44:45], v[130:131]
	s_cbranch_vccnz .LBB0_460
	v_max_f32_e32 v37, 0, v37
	v_max_f32_e32 v36, 0, v36
	v_max_f32_e32 v39, 0, v39
	v_max_f32_e32 v38, 0, v38
	v_max_f32_e32 v33, 0, v33
	v_max_f32_e32 v32, 0, v32
	v_max_f32_e32 v35, 0, v35
	v_max_f32_e32 v34, 0, v34
	v_pk_mul_f32 v[38:39], v[38:39], v[38:39]
	v_pk_mul_f32 v[36:37], v[36:37], v[36:37]
	v_pk_mul_f32 v[34:35], v[34:35], v[34:35]
	v_pk_mul_f32 v[32:33], v[32:33], v[32:33]
